# DIFF: five of the P.V(sub 1) V-fragment reads issued above the exp(sub 1) block
# baseline (speedup 1.0000x reference)
; #define MFMA(a, b, c) __builtin_amdgcn_mfma_f32_32x32x16_bf16((a), (b), (c), 0, 0, 0)
; DI u32 pk2(float a, float b) { f2_t v = {a, b}; bf2_t r = __builtin_convertvector(v, bf2_t); return __builtin_bit_cast(u32, r); }
; #define DIFF_MASK(sv, sub_) do { if (needmask) { _Pragma("unroll") for (int r = 0; r < 16; ++r) { const int kl_ = (sub_) * 32 + ((r < 8) ? (8 * g2 + r) : (16 + 8 * g2 + (r - 8))); \
;           if ((pki[kl_] >> 6) > (((int)qposf) >> 6)) sv[r] = -__builtin_inff(); } } } while (0)
; template <bool DIFF>
; DI void attn_phase(const AttnArgs& a, char* lds) {
;     ...
;           DIFF_ALIBI(s0, 0);
;           DIFF_MASK(s0, 0);
;           float ps = 0.f;
; #pragma unroll
;           for (int r = 0; r < 16; ++r) { s0[r] = __builtin_amdgcn_exp2f(s0[r]); ps += s0[r]; }
;           l_sum += ps;
;           asm volatile("" : "+v"(l_sum));
; #pragma unroll
;           for (int i = 0; i < NDS; ++i) { __builtin_amdgcn_sched_group_barrier(0x008, 1, 0); __builtin_amdgcn_sched_group_barrier(0x002, 9, 0); }
;         }
;         __builtin_amdgcn_sched_barrier(0);
;         {
;           bf16x8 vf[NM];
; #pragma unroll
;           for (int s2 = 0; s2 < 2; ++s2) {
; #pragma unroll
;             for (int m = 0; m < NM; ++m) vf[m] = *(const bf16x8*)(sb + voffb + m * 4096 + (((2 * s2) ^ vx) << 4));
;             u32x4 pw;
;             pw[0] = pk2(s0[8 * s2], s0[8 * s2 + 1]); pw[1] = pk2(s0[8 * s2 + 2], s0[8 * s2 + 3]);
;             pw[2] = pk2(s0[8 * s2 + 4], s0[8 * s2 + 5]); pw[3] = pk2(s0[8 * s2 + 6], s0[8 * s2 + 7]);
;             const bf16x8 pf = __builtin_bit_cast(bf16x8, pw);
; #pragma unroll
;             for (int m = 0; m < NM; ++m) o[m] = MFMA(vf[m], pf, o[m]);
;           }
;           DIFF_ALIBI(s1, 1);
;           DIFF_MASK(s1, 1);
.LBB0_605:
	v_exp_f32_e32 v11, v11
	v_exp_f32_e32 v9, v9
	v_exp_f32_e32 v10, v10
	v_exp_f32_e32 v8, v8
	v_bitop3_b32 v0, v0, v3, 7 bitop3:0x78
	v_add_f32_e32 v3, 0, v11
	v_exp_f32_e32 v165, v7
	v_add_f32_e32 v3, v9, v3
	v_exp_f32_e32 v166, v6
	v_add_f32_e32 v3, v10, v3
	v_exp_f32_e32 v167, v5
	v_add_f32_e32 v3, v8, v3
	v_exp_f32_e32 v168, v4
	v_add_f32_e32 v3, v165, v3
	v_exp_f32_e32 v164, v164
	v_lshlrev_b32_e32 v2, 7, v2
	v_add_f32_e32 v3, v166, v3
	v_exp_f32_e32 v169, v162
	v_and_b32_e32 v2, 0xf80, v2
	v_add_f32_e32 v3, v167, v3
	v_exp_f32_e32 v170, v160
	v_add_f32_e32 v3, v168, v3
	v_exp_f32_e32 v171, v161
	v_add_f32_e32 v3, v164, v3
	v_exp_f32_e32 v15, v15
	v_add_f32_e32 v3, v169, v3
	v_exp_f32_e32 v14, v14
	v_add_f32_e32 v3, v170, v3
	v_exp_f32_e32 v172, v13
	v_add_f32_e32 v3, v171, v3
	v_exp_f32_e32 v173, v12
	v_add_f32_e32 v3, v15, v3
	v_add_f32_e32 v3, v14, v3
	v_add_f32_e32 v3, v172, v3
	v_add_f32_e32 v3, v173, v3
	v_add_f32_e32 v162, v226, v3
	v_add_u32_e32 v160, s84, v2
	v_lshlrev_b32_e32 v161, 4, v0
	v_add_u32_e32 v0, v160, v161
	v_cvt_pk_bf16_f32 v6, v11, v9
	v_cvt_pk_bf16_f32 v7, v10, v8
	v_cvt_pk_bf16_f32 v8, v165, v166
	v_cvt_pk_bf16_f32 v9, v167, v168
	v_cvt_pk_bf16_f32 v10, v164, v169
	v_cvt_pk_bf16_f32 v11, v170, v171
	v_cvt_pk_bf16_f32 v12, v15, v14
	v_cvt_pk_bf16_f32 v13, v172, v173
	v_add_u32_e32 v14, 0x10180, v227
	v_xad_u32 v15, v161, 32, v160
	ds_read_b128 v[164:167], v14
	ds_read_b128 v[168:171], v14 offset:16
	ds_read_b128 v[172:175], v14 offset:64
	ds_read_b128 v[248:251], v14 offset:80
	ds_read_b128 v[2:5], v0 offset:32768
	ds_read_b128 v[228:231], v0 offset:36864
	ds_read_b128 v[232:235], v0 offset:40960
	ds_read_b128 v[236:239], v0 offset:45056
	ds_read_b128 v[240:243], v0 offset:49152
	ds_read_b128 v[244:247], v0 offset:53248
	s_and_b64 vcc, exec, s[8:9]
	s_waitcnt lgkmcnt(5)
	v_mfma_f32_32x32x16_bf16 v[128:143], v[2:5], v[6:9], v[128:143]
	ds_read_b128 v[2:5], v0 offset:57344
	v_sub_f32_e32 v164, v221, v164
	v_sub_f32_e32 v165, v221, v165
	s_waitcnt lgkmcnt(5)
	v_mfma_f32_32x32x16_bf16 v[112:127], v[228:231], v[6:9], v[112:127]
	ds_read_b128 v[228:231], v0 offset:61440
	v_sub_f32_e32 v166, v221, v166
	v_sub_f32_e32 v167, v221, v167
	s_waitcnt lgkmcnt(5)
	v_mfma_f32_32x32x16_bf16 v[96:111], v[232:235], v[6:9], v[96:111]
	ds_read_b128 v[232:235], v15 offset:32768
	v_sub_f32_e32 v168, v221, v168
	v_sub_f32_e32 v169, v221, v169
	s_waitcnt lgkmcnt(5)
	v_mfma_f32_32x32x16_bf16 v[80:95], v[236:239], v[6:9], v[80:95]
	ds_read_b128 v[236:239], v15 offset:36864
	v_sub_f32_e32 v170, v221, v170
	v_sub_f32_e32 v171, v221, v171
	s_waitcnt lgkmcnt(5)
	v_mfma_f32_32x32x16_bf16 v[64:79], v[240:243], v[6:9], v[64:79]
	ds_read_b128 v[240:243], v15 offset:40960
	v_sub_f32_e32 v172, v221, v172
	v_sub_f32_e32 v173, v221, v173
	s_waitcnt lgkmcnt(5)
	v_mfma_f32_32x32x16_bf16 v[48:63], v[244:247], v[6:9], v[48:63]
	ds_read_b128 v[244:247], v15 offset:45056
	v_sub_f32_e32 v174, v221, v174
	v_sub_f32_e32 v175, v221, v175
	s_waitcnt lgkmcnt(5)
	v_mfma_f32_32x32x16_bf16 v[32:47], v[2:5], v[6:9], v[32:47]
	ds_read_b128 v[2:5], v15 offset:49152
	v_sub_f32_e32 v248, v221, v248
	v_sub_f32_e32 v249, v221, v249
	s_waitcnt lgkmcnt(5)
	v_mfma_f32_32x32x16_bf16 v[16:31], v[228:231], v[6:9], v[16:31]
	ds_read_b128 v[228:231], v15 offset:53248
	v_sub_f32_e32 v250, v221, v250
	v_sub_f32_e32 v251, v221, v251
	s_waitcnt lgkmcnt(5)
	v_mfma_f32_32x32x16_bf16 v[128:143], v[232:235], v[10:13], v[128:143]
	ds_read_b128 v[232:235], v15 offset:57344
	v_fma_f32 v164, -v223, |v164|, v144
	v_fma_f32 v165, -v223, |v165|, v145
	s_waitcnt lgkmcnt(5)
	v_mfma_f32_32x32x16_bf16 v[112:127], v[236:239], v[10:13], v[112:127]
	ds_read_b128 v[236:239], v15 offset:61440
	v_fma_f32 v166, -v223, |v166|, v146
	v_fma_f32 v167, -v223, |v167|, v147
	s_waitcnt lgkmcnt(5)
	v_mfma_f32_32x32x16_bf16 v[96:111], v[240:243], v[10:13], v[96:111]
	v_fma_f32 v168, -v223, |v168|, v148
	v_fma_f32 v169, -v223, |v169|, v149
	s_waitcnt lgkmcnt(4)
	v_mfma_f32_32x32x16_bf16 v[80:95], v[244:247], v[10:13], v[80:95]
	v_fma_f32 v170, -v223, |v170|, v150
	v_fma_f32 v171, -v223, |v171|, v151
	s_waitcnt lgkmcnt(3)
	v_mfma_f32_32x32x16_bf16 v[64:79], v[2:5], v[10:13], v[64:79]
	v_fma_f32 v172, -v223, |v172|, v152
	v_fma_f32 v173, -v223, |v173|, v153
	s_waitcnt lgkmcnt(2)
	v_mfma_f32_32x32x16_bf16 v[48:63], v[228:231], v[10:13], v[48:63]
	v_fma_f32 v174, -v223, |v174|, v154
	v_fma_f32 v175, -v223, |v175|, v155
	s_waitcnt lgkmcnt(1)
	v_mfma_f32_32x32x16_bf16 v[32:47], v[232:235], v[10:13], v[32:47]
	v_fma_f32 v248, -v223, |v248|, v156
	v_fma_f32 v249, -v223, |v249|, v157
	s_waitcnt lgkmcnt(0)
	v_mfma_f32_32x32x16_bf16 v[16:31], v[236:239], v[10:13], v[16:31]
	v_fma_f32 v250, -v223, |v250|, v158
	v_fma_f32 v251, -v223, |v251|, v159
	v_xad_u32 v156, v161, 64, v160
	ds_read_b128 v[228:231], v156 offset:36864
	ds_read_b128 v[232:235], v156 offset:40960
	ds_read_b128 v[236:239], v156 offset:45056
	ds_read_b128 v[240:243], v156 offset:49152
	ds_read_b128 v[244:247], v156 offset:53248
	s_cbranch_vccnz .LBB0_607
; #define MFMA(a, b, c) __builtin_amdgcn_mfma_f32_32x32x16_bf16((a), (b), (c), 0, 0, 0)
; DI u32 pk2(float a, float b) { f2_t v = {a, b}; bf2_t r = __builtin_convertvector(v, bf2_t); return __builtin_bit_cast(u32, r); }
; #define DIFF_MASK(sv, sub_) do { if (needmask) { _Pragma("unroll") for (int r = 0; r < 16; ++r) { const int kl_ = (sub_) * 32 + ((r < 8) ? (8 * g2 + r) : (16 + 8 * g2 + (r - 8))); \
;           if ((pki[kl_] >> 6) > (((int)qposf) >> 6)) sv[r] = -__builtin_inff(); } } } while (0)
; template <bool DIFF>
; DI void attn_phase(const AttnArgs& a, char* lds) {
;     ...
;           DIFF_MASK(s1, 1);
;           float ps = 0.f;
; #pragma unroll
;           for (int r = 0; r < 16; ++r) { s1[r] = __builtin_amdgcn_exp2f(s1[r]); ps += s1[r]; }
;           l_sum += ps;
;           asm volatile("" : "+v"(l_sum));
; #pragma unroll
;           for (int i = 0; i < 2 * NM; ++i) { __builtin_amdgcn_sched_group_barrier(0x008, 1, 0); __builtin_amdgcn_sched_group_barrier(0x002, 4, 0); }
;         }
;         __builtin_amdgcn_sched_barrier(0);
;         {
; #pragma unroll
;           for (int s2 = 0; s2 < 2; ++s2) {
;             bf16x8 vf[NM];
; #pragma unroll
;             for (int m = 0; m < NM; ++m) vf[m] = *(const bf16x8*)(sb + voffb + m * 4096 + (((4 + 2 * s2) ^ vx) << 4));
;             u32x4 pw;
;             pw[0] = pk2(s1[8 * s2], s1[8 * s2 + 1]); pw[1] = pk2(s1[8 * s2 + 2], s1[8 * s2 + 3]);
;             pw[2] = pk2(s1[8 * s2 + 4], s1[8 * s2 + 5]); pw[3] = pk2(s1[8 * s2 + 6], s1[8 * s2 + 7]);
;             const bf16x8 pf = __builtin_bit_cast(bf16x8, pw);
; #pragma unroll
;             for (int m = 0; m < NM; ++m) o[m] = MFMA(vf[m], pf, o[m]);
;           }
;         }
	ds_read_b128 v[146:149], v163 offset:128
	s_waitcnt lgkmcnt(0)
	v_ashrrev_i32_e32 v144, 6, v146
	v_cmp_le_i32_e32 vcc, v144, v224
	v_ashrrev_i32_e32 v144, 6, v147
	s_nop 0
	v_cndmask_b32_e32 v164, v216, v164, vcc
	v_cmp_le_i32_e32 vcc, v144, v224
	v_ashrrev_i32_e32 v144, 6, v148
	s_nop 0
	v_cndmask_b32_e32 v165, v216, v165, vcc
	v_cmp_le_i32_e32 vcc, v144, v224
	v_ashrrev_i32_e32 v144, 6, v149
	s_nop 0
	v_cndmask_b32_e32 v166, v216, v166, vcc
	v_cmp_le_i32_e32 vcc, v144, v224
	v_add_u32_e32 v144, 0x10090, v227
	ds_read_b128 v[146:149], v144
	v_cndmask_b32_e32 v167, v216, v167, vcc
	s_waitcnt lgkmcnt(0)
	v_ashrrev_i32_e32 v144, 6, v146
	v_cmp_le_i32_e32 vcc, v144, v224
	v_ashrrev_i32_e32 v144, 6, v147
	s_nop 0
	v_cndmask_b32_e32 v168, v216, v168, vcc
	v_cmp_le_i32_e32 vcc, v144, v224
	v_ashrrev_i32_e32 v144, 6, v148
	s_nop 0
	v_cndmask_b32_e32 v169, v216, v169, vcc
	v_cmp_le_i32_e32 vcc, v144, v224
	v_ashrrev_i32_e32 v144, 6, v149
	s_nop 0
	v_cndmask_b32_e32 v170, v216, v170, vcc
	v_cmp_le_i32_e32 vcc, v144, v224
	v_add_u32_e32 v144, 0x100c0, v227
	ds_read_b128 v[146:149], v144
	v_cndmask_b32_e32 v171, v216, v171, vcc
	s_waitcnt lgkmcnt(0)
	v_ashrrev_i32_e32 v144, 6, v146
	v_cmp_le_i32_e32 vcc, v144, v224
	v_ashrrev_i32_e32 v144, 6, v147
	s_nop 0
	v_cndmask_b32_e32 v172, v216, v172, vcc
	v_cmp_le_i32_e32 vcc, v144, v224
	v_ashrrev_i32_e32 v144, 6, v148
	s_nop 0
	v_cndmask_b32_e32 v173, v216, v173, vcc
	v_cmp_le_i32_e32 vcc, v144, v224
	v_ashrrev_i32_e32 v144, 6, v149
	s_nop 0
	v_cndmask_b32_e32 v174, v216, v174, vcc
	v_cmp_le_i32_e32 vcc, v144, v224
	v_add_u32_e32 v144, 0x100d0, v227
	ds_read_b128 v[146:149], v144
	v_cndmask_b32_e32 v175, v216, v175, vcc
	s_waitcnt lgkmcnt(0)
	v_ashrrev_i32_e32 v144, 6, v146
	v_cmp_le_i32_e32 vcc, v144, v224
	v_ashrrev_i32_e32 v144, 6, v147
	s_nop 0
	v_cndmask_b32_e32 v248, v216, v248, vcc
	v_cmp_le_i32_e32 vcc, v144, v224
	v_ashrrev_i32_e32 v144, 6, v148
	s_nop 0
	v_cndmask_b32_e32 v249, v216, v249, vcc
	v_cmp_le_i32_e32 vcc, v144, v224
	v_ashrrev_i32_e32 v144, 6, v149
	s_nop 0
	v_cndmask_b32_e32 v250, v216, v250, vcc
	v_cmp_le_i32_e32 vcc, v144, v224
	s_nop 1
	v_cndmask_b32_e32 v251, v216, v251, vcc
.LBB0_607:
	v_exp_f32_e32 v0, v164
	v_exp_f32_e32 v9, v165
	v_exp_f32_e32 v144, v166
	v_exp_f32_e32 v146, v167
	v_add_f32_e32 v2, 0, v0
	v_exp_f32_e32 v147, v168
	v_add_f32_e32 v2, v9, v2
	v_exp_f32_e32 v148, v169
	v_add_f32_e32 v2, v144, v2
	v_exp_f32_e32 v149, v170
	v_add_f32_e32 v2, v146, v2
	v_exp_f32_e32 v150, v171
	v_add_f32_e32 v2, v147, v2
	v_exp_f32_e32 v151, v172
	v_add_f32_e32 v2, v148, v2
	v_exp_f32_e32 v145, v173
	v_add_f32_e32 v2, v149, v2
	v_exp_f32_e32 v152, v174
	v_add_f32_e32 v2, v150, v2
	v_exp_f32_e32 v153, v175
	v_add_f32_e32 v2, v151, v2
	v_exp_f32_e32 v154, v248
	v_add_f32_e32 v2, v145, v2
	v_exp_f32_e32 v155, v249
	v_add_f32_e32 v2, v152, v2
	v_exp_f32_e32 v14, v250
	v_add_f32_e32 v2, v153, v2
	v_exp_f32_e32 v15, v251
	v_add_f32_e32 v2, v154, v2
	v_add_f32_e32 v2, v155, v2
	v_add_f32_e32 v2, v14, v2
	v_add_f32_e32 v2, v15, v2
	v_add_f32_e32 v226, v162, v2
	ds_read_b128 v[2:5], v156 offset:32768
	ds_read_b128 v[248:251], v156 offset:57344
	v_cvt_pk_bf16_f32 v6, v0, v9
	v_cvt_pk_bf16_f32 v7, v144, v146
	v_cvt_pk_bf16_f32 v8, v147, v148
	v_cvt_pk_bf16_f32 v9, v149, v150
	v_xad_u32 v0, v161, s74, v160
	v_cvt_pk_bf16_f32 v10, v151, v145
	v_cvt_pk_bf16_f32 v11, v152, v153
	v_cvt_pk_bf16_f32 v12, v154, v155
	v_cvt_pk_bf16_f32 v13, v14, v15
	s_waitcnt lgkmcnt(1)
	v_mfma_f32_32x32x16_bf16 v[128:143], v[2:5], v[6:9], v[128:143]
	ds_read_b128 v[2:5], v156 offset:61440
	s_waitcnt lgkmcnt(6)
	v_mfma_f32_32x32x16_bf16 v[112:127], v[228:231], v[6:9], v[112:127]
	ds_read_b128 v[228:231], v0 offset:32768
	s_waitcnt lgkmcnt(6)
	v_mfma_f32_32x32x16_bf16 v[96:111], v[232:235], v[6:9], v[96:111]
	ds_read_b128 v[232:235], v0 offset:36864
	s_waitcnt lgkmcnt(6)
	v_mfma_f32_32x32x16_bf16 v[80:95], v[236:239], v[6:9], v[80:95]
	ds_read_b128 v[236:239], v0 offset:40960
	s_waitcnt lgkmcnt(6)
	v_mfma_f32_32x32x16_bf16 v[64:79], v[240:243], v[6:9], v[64:79]
	ds_read_b128 v[240:243], v0 offset:45056
	s_waitcnt lgkmcnt(6)
	v_mfma_f32_32x32x16_bf16 v[48:63], v[244:247], v[6:9], v[48:63]
	ds_read_b128 v[244:247], v0 offset:49152
	s_waitcnt lgkmcnt(6)
	v_mfma_f32_32x32x16_bf16 v[32:47], v[248:251], v[6:9], v[32:47]
	ds_read_b128 v[248:251], v0 offset:53248
	s_waitcnt lgkmcnt(6)
	v_mfma_f32_32x32x16_bf16 v[16:31], v[2:5], v[6:9], v[16:31]
	ds_read_b128 v[2:5], v0 offset:57344
	s_waitcnt lgkmcnt(6)
	v_mfma_f32_32x32x16_bf16 v[128:143], v[228:231], v[10:13], v[128:143]
	ds_read_b128 v[228:231], v0 offset:61440
	s_waitcnt lgkmcnt(6)
	v_mfma_f32_32x32x16_bf16 v[112:127], v[232:235], v[10:13], v[112:127]
	s_waitcnt lgkmcnt(5)
	v_mfma_f32_32x32x16_bf16 v[96:111], v[236:239], v[10:13], v[96:111]
	s_waitcnt lgkmcnt(4)
	v_mfma_f32_32x32x16_bf16 v[80:95], v[240:243], v[10:13], v[80:95]
	s_waitcnt lgkmcnt(3)
	v_mfma_f32_32x32x16_bf16 v[64:79], v[244:247], v[10:13], v[64:79]
	s_waitcnt lgkmcnt(2)
	v_mfma_f32_32x32x16_bf16 v[48:63], v[248:251], v[10:13], v[48:63]
	s_waitcnt lgkmcnt(1)
	v_mfma_f32_32x32x16_bf16 v[32:47], v[2:5], v[10:13], v[32:47]
	s_waitcnt lgkmcnt(0)
	v_mfma_f32_32x32x16_bf16 v[16:31], v[228:231], v[10:13], v[16:31]
